# band item epilogue moved into the idle tile steps of each wave (loads at step qc+9, compute at qc+10), shared text with scalar return selector
# baseline (speedup 1.0000x reference)
; __device__ __forceinline__ void b_item(const Params& P, int layer, LAS unsigned char* lds, int item, int tid) {
;     ...
; #pragma unroll 1
;     for (int j = jst; j < 12; ++j) {
;         const int buf = (j - jst) & 1;
;         asm volatile("s_waitcnt vmcnt(0)" ::: "memory");
;         __syncthreads();
;         if (j + 1 < 12) B_DMA(j + 1, buf ^ 1);
;         step(j, KV + buf * 32768, KV + buf * 32768 + 16384);
;     }
;     __syncthreads();
.LBB0_140:
	v_readfirstlane_b32 s58, v207
	s_nop 1
	s_cmp_lt_u32 s58, 10
	s_cbranch_scc1 .Lepi_exit_done
	s_cmp_eq_u32 s58, 10
	s_cbranch_scc1 .Lepi_exit_b
	s_mov_b32 s58, 2
	s_branch .Lepi_A
.Lepi_exit_b:
	s_waitcnt lgkmcnt(0)
	s_barrier
	s_waitcnt vmcnt(0)
	s_mov_b32 s58, 1
	s_branch .Lepi_B
.Lepi_exit_done:
	s_waitcnt lgkmcnt(0)
	s_barrier
	s_mov_b64 s[0:1], 0
	s_branch .LBB0_141
.Lepi_hook_a:
	s_mov_b32 s58, 0

; __device__ __forceinline__ float rcp_f(float v) { return __builtin_amdgcn_rcpf(v); }
; __device__ __forceinline__ void b_item(const Params& P, int layer, LAS unsigned char* lds, int item, int tid) {
;     ...
;     for (int u = 0; u < 2; ++u) {
;         float l = lrun[u]; l += __shfl_xor(l, 16); l += __shfl_xor(l, 32);
;         const float inv = rcp_f(l);
;         const size_t tok = tok0 + 64 * qc + 32 * th + 16 * u + c15;
;         const bf16_t* gate = pjp(proj, BG, 128, h, tok);
;         bf16_t* y = (bf16_t*)(P.ws + (layer == 0 ? WS_H : WS_D1)) + tok * DM + YB + h * 128;
; #pragma unroll
;         for (int vb = 0; vb < 8; ++vb) { const int v0 = 16 * vb + 4 * g; const u32x2 gt2 = *(const u32x2*)(gate + v0);
.Lbq_ep_skip:
	s_or_b64 exec, exec, s[14:15]
	v_or_b32_e32 v162, 16, v64
	v_mov_b32_e32 v163, v65
	v_lshl_add_u64 v[162:163], v[162:163], 0, s[12:13]
	v_lshlrev_b64 v[162:163], 8, v[162:163]
	v_lshl_add_u64 v[162:163], v[156:157], 0, v[162:163]
	global_load_dwordx2 v[84:85], v[70:71], off
	global_load_dwordx2 v[86:87], v[70:71], off offset:32
	global_load_dwordx2 v[88:89], v[70:71], off offset:64
	global_load_dwordx2 v[90:91], v[70:71], off offset:96
	global_load_dwordx2 v[92:93], v[70:71], off offset:128
	global_load_dwordx2 v[94:95], v[70:71], off offset:160
	global_load_dwordx2 v[164:165], v[70:71], off offset:192
	global_load_dwordx2 v[166:167], v[70:71], off offset:224
	global_load_dwordx2 v[168:169], v[162:163], off
	global_load_dwordx2 v[170:171], v[162:163], off offset:32
	global_load_dwordx2 v[172:173], v[162:163], off offset:64
	global_load_dwordx2 v[174:175], v[162:163], off offset:96
	global_load_dwordx2 v[228:229], v[162:163], off offset:128
	global_load_dwordx2 v[230:231], v[162:163], off offset:160
	global_load_dwordx2 v[226:227], v[162:163], off offset:192
	global_load_dwordx2 v[162:163], v[162:163], off offset:224
	s_cmp_eq_u32 s58, 2
	s_cbranch_scc1 .Lepi_exit_b
	s_branch .Lepi_loop_ret

; __device__ __forceinline__ unsigned cvt_pk_bf16(float lo, float hi) { const f32x2 f = {lo, hi}; const bf16x2_t v = __builtin_convertvector(f, bf16x2_t); return __builtin_bit_cast(unsigned, v); }
; __device__ __forceinline__ float bflo(unsigned u) { return __uint_as_float(u << 16); }
; __device__ __forceinline__ float bfhi(unsigned u) { return __uint_as_float(u & 0xffff0000u); }
; __device__ __forceinline__ float rcp_f(float v) { return __builtin_amdgcn_rcpf(v); }
; __device__ __forceinline__ float silu_f(float v) { return v * rcp_f(1.f + __expf(-v)); }
; __device__ __forceinline__ void b_item(const Params& P, int layer, LAS unsigned char* lds, int item, int tid) {
;     ...
;     for (int u = 0; u < 2; ++u) {
;         float l = lrun[u]; l += __shfl_xor(l, 16); l += __shfl_xor(l, 32);
;         const float inv = rcp_f(l);
;         const size_t tok = tok0 + 64 * qc + 32 * th + 16 * u + c15;
;         const bf16_t* gate = pjp(proj, BG, 128, h, tok);
;         bf16_t* y = (bf16_t*)(P.ws + (layer == 0 ? WS_H : WS_D1)) + tok * DM + YB + h * 128;
; #pragma unroll
;         for (int vb = 0; vb < 8; ++vb) { const int v0 = 16 * vb + 4 * g; const u32x2 gt2 = *(const u32x2*)(gate + v0);
;             u32x2 o; o.x = cvt_pk_bf16(acco[u][vb][0] * inv * silu_f(bflo(gt2.x)), acco[u][vb][1] * inv * silu_f(bfhi(gt2.x)));
;             o.y = cvt_pk_bf16(acco[u][vb][2] * inv * silu_f(bflo(gt2.y)), acco[u][vb][3] * inv * silu_f(bfhi(gt2.y)));
;             *(u32x2*)(y + v0) = o; }
.Lepi_B:
	v_lshl_add_u64 v[64:65], s[50:51], 0, v[152:153]
	v_or_b32_e32 v64, v64, v154
	v_and_b32_e32 v67, 64, v184
	v_xor_b32_e32 v66, 16, v184
	v_add_u32_e32 v67, 64, v67
	v_cmp_lt_i32_e32 vcc, v66, v67
	v_xor_b32_e32 v68, 32, v184
	s_lshl_b32 s0, s10, 7
	v_cndmask_b32_e32 v66, v184, v66, vcc
	v_lshlrev_b32_e32 v69, 2, v66
	ds_bpermute_b32 v73, v69, v225
	v_cmp_lt_i32_e32 vcc, v68, v67
	s_ashr_i32 s1, s0, 31
	v_lshlrev_b64 v[66:67], 12, v[64:65]
	v_cndmask_b32_e32 v68, v184, v68, vcc
	v_lshlrev_b32_e32 v72, 2, v68
	s_waitcnt lgkmcnt(0)
	v_add_f32_e32 v68, v225, v73
	ds_bpermute_b32 v73, v72, v68
	s_lshl_b64 s[0:1], s[0:1], 1
	v_lshl_add_u64 v[66:67], s[18:19], 0, v[66:67]
	v_lshl_add_u64 v[66:67], v[66:67], 0, s[0:1]
	v_lshl_add_u64 v[66:67], v[66:67], 0, v[136:137]
	s_waitcnt lgkmcnt(0)
	v_add_f32_e32 v68, v68, v73
	v_rcp_f32_e32 v68, v68
	v_or_b32_e32 v64, 16, v64
	v_pk_mul_f32 v[60:61], v[60:61], v[68:69] op_sel_hi:[1,0]
	v_pk_mul_f32 v[62:63], v[62:63], v[68:69] op_sel_hi:[1,0]
	v_pk_mul_f32 v[56:57], v[56:57], v[68:69] op_sel_hi:[1,0]
	v_pk_mul_f32 v[58:59], v[58:59], v[68:69] op_sel_hi:[1,0]
	v_pk_mul_f32 v[52:53], v[52:53], v[68:69] op_sel_hi:[1,0]
	v_pk_mul_f32 v[54:55], v[54:55], v[68:69] op_sel_hi:[1,0]
	v_pk_mul_f32 v[48:49], v[48:49], v[68:69] op_sel_hi:[1,0]
	v_pk_mul_f32 v[50:51], v[50:51], v[68:69] op_sel_hi:[1,0]
	v_pk_mul_f32 v[44:45], v[44:45], v[68:69] op_sel_hi:[1,0]
	v_pk_mul_f32 v[46:47], v[46:47], v[68:69] op_sel_hi:[1,0]
	v_pk_mul_f32 v[40:41], v[40:41], v[68:69] op_sel_hi:[1,0]
	v_pk_mul_f32 v[42:43], v[42:43], v[68:69] op_sel_hi:[1,0]
	v_pk_mul_f32 v[36:37], v[36:37], v[68:69] op_sel_hi:[1,0]
	v_pk_mul_f32 v[38:39], v[38:39], v[68:69] op_sel_hi:[1,0]
	v_pk_mul_f32 v[32:33], v[32:33], v[68:69] op_sel_hi:[1,0]
	v_pk_mul_f32 v[34:35], v[34:35], v[68:69] op_sel_hi:[1,0]
	v_lshlrev_b32_e32 v76, 16, v84
	v_and_b32_e32 v77, 0xffff0000, v84
	v_lshlrev_b32_e32 v74, 16, v85
	v_and_b32_e32 v75, 0xffff0000, v85
	v_mul_f32_e32 v73, 0xbfb8aa3b, v76
	v_mul_f32_e32 v78, 0xbfb8aa3b, v77
	v_mul_f32_e32 v79, 0xbfb8aa3b, v74
	v_mul_f32_e32 v80, 0xbfb8aa3b, v75
	v_exp_f32_e32 v73, v73
	v_exp_f32_e32 v78, v78
	v_exp_f32_e32 v79, v79
	v_exp_f32_e32 v80, v80
	v_add_f32_e32 v73, 1.0, v73
	v_add_f32_e32 v81, 1.0, v78
	v_add_f32_e32 v82, 1.0, v79
	v_add_f32_e32 v83, 1.0, v80
	v_rcp_f32_e32 v78, v73
	v_rcp_f32_e32 v79, v81
	v_rcp_f32_e32 v80, v82
	v_rcp_f32_e32 v81, v83
	v_pk_mul_f32 v[76:77], v[78:79], v[76:77]
	s_nop 0
	v_pk_mul_f32 v[60:61], v[60:61], v[76:77]
	v_pk_mul_f32 v[74:75], v[80:81], v[74:75]
	v_cvt_pk_bf16_f32 v60, v60, v61
	v_pk_mul_f32 v[62:63], v[62:63], v[74:75]
	s_nop 0
	v_cvt_pk_bf16_f32 v61, v62, v63
	global_store_dwordx2 v[66:67], v[60:61], off offset:1536
	v_lshlrev_b32_e32 v62, 16, v86
	v_and_b32_e32 v63, 0xffff0000, v86
	v_lshlrev_b32_e32 v60, 16, v87
	v_and_b32_e32 v61, 0xffff0000, v87
	v_mul_f32_e32 v73, 0xbfb8aa3b, v62
	v_mul_f32_e32 v74, 0xbfb8aa3b, v63
	v_mul_f32_e32 v75, 0xbfb8aa3b, v60
	v_mul_f32_e32 v76, 0xbfb8aa3b, v61
	v_exp_f32_e32 v73, v73
	v_exp_f32_e32 v74, v74
	v_exp_f32_e32 v75, v75
	v_exp_f32_e32 v76, v76
	v_add_f32_e32 v73, 1.0, v73
	v_add_f32_e32 v77, 1.0, v74
	v_add_f32_e32 v78, 1.0, v75
	v_add_f32_e32 v79, 1.0, v76
	v_rcp_f32_e32 v74, v73
	v_rcp_f32_e32 v75, v77
	v_rcp_f32_e32 v76, v78
	v_rcp_f32_e32 v77, v79
	v_pk_mul_f32 v[62:63], v[74:75], v[62:63]
	s_nop 0
	v_pk_mul_f32 v[56:57], v[56:57], v[62:63]
	v_pk_mul_f32 v[60:61], v[76:77], v[60:61]
	v_cvt_pk_bf16_f32 v56, v56, v57
	v_pk_mul_f32 v[58:59], v[58:59], v[60:61]
	s_nop 0
	v_cvt_pk_bf16_f32 v57, v58, v59
	global_store_dwordx2 v[66:67], v[56:57], off offset:1568
	v_lshlrev_b32_e32 v58, 16, v88
	v_and_b32_e32 v59, 0xffff0000, v88
	v_lshlrev_b32_e32 v56, 16, v89
	v_and_b32_e32 v57, 0xffff0000, v89
	v_mul_f32_e32 v60, 0xbfb8aa3b, v58
	v_mul_f32_e32 v61, 0xbfb8aa3b, v59
	v_mul_f32_e32 v62, 0xbfb8aa3b, v56
	v_mul_f32_e32 v63, 0xbfb8aa3b, v57
	v_exp_f32_e32 v60, v60
	v_exp_f32_e32 v61, v61
	v_exp_f32_e32 v62, v62
	v_exp_f32_e32 v63, v63
	v_add_f32_e32 v60, 1.0, v60
	v_add_f32_e32 v61, 1.0, v61
	v_add_f32_e32 v62, 1.0, v62
	v_add_f32_e32 v63, 1.0, v63
	v_rcp_f32_e32 v60, v60
	v_rcp_f32_e32 v61, v61
	v_rcp_f32_e32 v62, v62
	v_rcp_f32_e32 v63, v63
	v_pk_mul_f32 v[58:59], v[60:61], v[58:59]
	s_nop 0
	v_pk_mul_f32 v[52:53], v[52:53], v[58:59]
	v_pk_mul_f32 v[56:57], v[62:63], v[56:57]
	v_cvt_pk_bf16_f32 v52, v52, v53
	v_pk_mul_f32 v[54:55], v[54:55], v[56:57]
	s_nop 0
	v_cvt_pk_bf16_f32 v53, v54, v55
	global_store_dwordx2 v[66:67], v[52:53], off offset:1600
	v_lshlrev_b32_e32 v54, 16, v90
	v_and_b32_e32 v55, 0xffff0000, v90
	v_lshlrev_b32_e32 v52, 16, v91
	v_and_b32_e32 v53, 0xffff0000, v91
	v_mul_f32_e32 v56, 0xbfb8aa3b, v54
	v_mul_f32_e32 v57, 0xbfb8aa3b, v55
	v_mul_f32_e32 v58, 0xbfb8aa3b, v52
	v_mul_f32_e32 v59, 0xbfb8aa3b, v53
	v_exp_f32_e32 v56, v56
	v_exp_f32_e32 v57, v57
	v_exp_f32_e32 v58, v58
	v_exp_f32_e32 v59, v59
	v_add_f32_e32 v56, 1.0, v56
	v_add_f32_e32 v57, 1.0, v57
	v_add_f32_e32 v58, 1.0, v58
	v_add_f32_e32 v59, 1.0, v59
	v_rcp_f32_e32 v56, v56
	v_rcp_f32_e32 v57, v57
	v_rcp_f32_e32 v58, v58
	v_rcp_f32_e32 v59, v59
	v_pk_mul_f32 v[54:55], v[56:57], v[54:55]
	s_nop 0
	v_pk_mul_f32 v[48:49], v[48:49], v[54:55]
	v_pk_mul_f32 v[52:53], v[58:59], v[52:53]
	v_cvt_pk_bf16_f32 v48, v48, v49
	v_pk_mul_f32 v[50:51], v[50:51], v[52:53]
	s_nop 0
	v_cvt_pk_bf16_f32 v49, v50, v51
	global_store_dwordx2 v[66:67], v[48:49], off offset:1632
	v_lshlrev_b32_e32 v50, 16, v92
	v_and_b32_e32 v51, 0xffff0000, v92
	v_lshlrev_b32_e32 v48, 16, v93
	v_and_b32_e32 v49, 0xffff0000, v93
	v_mul_f32_e32 v52, 0xbfb8aa3b, v50
	v_mul_f32_e32 v53, 0xbfb8aa3b, v51
; __device__ __forceinline__ unsigned cvt_pk_bf16(float lo, float hi) { const f32x2 f = {lo, hi}; const bf16x2_t v = __builtin_convertvector(f, bf16x2_t); return __builtin_bit_cast(unsigned, v); }
; __device__ __forceinline__ float bflo(unsigned u) { return __uint_as_float(u << 16); }
; __device__ __forceinline__ float bfhi(unsigned u) { return __uint_as_float(u & 0xffff0000u); }
; __device__ __forceinline__ float rcp_f(float v) { return __builtin_amdgcn_rcpf(v); }
; __device__ __forceinline__ float silu_f(float v) { return v * rcp_f(1.f + __expf(-v)); }
; __device__ __forceinline__ void b_item(const Params& P, int layer, LAS unsigned char* lds, int item, int tid) {
;     ...
;     for (int u = 0; u < 2; ++u) {
;         float l = lrun[u]; l += __shfl_xor(l, 16); l += __shfl_xor(l, 32);
;         const float inv = rcp_f(l);
;         const size_t tok = tok0 + 64 * qc + 32 * th + 16 * u + c15;
;         const bf16_t* gate = pjp(proj, BG, 128, h, tok);
;         bf16_t* y = (bf16_t*)(P.ws + (layer == 0 ? WS_H : WS_D1)) + tok * DM + YB + h * 128;
; #pragma unroll
;         for (int vb = 0; vb < 8; ++vb) { const int v0 = 16 * vb + 4 * g; const u32x2 gt2 = *(const u32x2*)(gate + v0);
;             u32x2 o; o.x = cvt_pk_bf16(acco[u][vb][0] * inv * silu_f(bflo(gt2.x)), acco[u][vb][1] * inv * silu_f(bfhi(gt2.x)));
;             o.y = cvt_pk_bf16(acco[u][vb][2] * inv * silu_f(bflo(gt2.y)), acco[u][vb][3] * inv * silu_f(bfhi(gt2.y)));
;             *(u32x2*)(y + v0) = o; }
	v_mul_f32_e32 v54, 0xbfb8aa3b, v48
	v_mul_f32_e32 v55, 0xbfb8aa3b, v49
	v_exp_f32_e32 v52, v52
	v_exp_f32_e32 v53, v53
	v_exp_f32_e32 v54, v54
	v_exp_f32_e32 v55, v55
	v_add_f32_e32 v52, 1.0, v52
	v_add_f32_e32 v53, 1.0, v53
	v_add_f32_e32 v54, 1.0, v54
	v_add_f32_e32 v55, 1.0, v55
	v_rcp_f32_e32 v52, v52
	v_rcp_f32_e32 v53, v53
	v_rcp_f32_e32 v54, v54
	v_rcp_f32_e32 v55, v55
	v_pk_mul_f32 v[50:51], v[52:53], v[50:51]
	s_nop 0
	v_pk_mul_f32 v[44:45], v[44:45], v[50:51]
	v_pk_mul_f32 v[48:49], v[54:55], v[48:49]
	v_cvt_pk_bf16_f32 v44, v44, v45
	v_pk_mul_f32 v[46:47], v[46:47], v[48:49]
	s_nop 0
	v_cvt_pk_bf16_f32 v45, v46, v47
	global_store_dwordx2 v[66:67], v[44:45], off offset:1664
	v_lshlrev_b32_e32 v46, 16, v94
	v_and_b32_e32 v47, 0xffff0000, v94
	v_lshlrev_b32_e32 v44, 16, v95
	v_and_b32_e32 v45, 0xffff0000, v95
	v_mul_f32_e32 v48, 0xbfb8aa3b, v46
	v_mul_f32_e32 v49, 0xbfb8aa3b, v47
	v_mul_f32_e32 v50, 0xbfb8aa3b, v44
	v_mul_f32_e32 v51, 0xbfb8aa3b, v45
	v_exp_f32_e32 v48, v48
	v_exp_f32_e32 v49, v49
	v_exp_f32_e32 v50, v50
	v_exp_f32_e32 v51, v51
	v_add_f32_e32 v48, 1.0, v48
	v_add_f32_e32 v49, 1.0, v49
	v_add_f32_e32 v50, 1.0, v50
	v_add_f32_e32 v51, 1.0, v51
	v_rcp_f32_e32 v48, v48
	v_rcp_f32_e32 v49, v49
	v_rcp_f32_e32 v50, v50
	v_rcp_f32_e32 v51, v51
	v_pk_mul_f32 v[46:47], v[48:49], v[46:47]
	s_nop 0
	v_pk_mul_f32 v[40:41], v[40:41], v[46:47]
	v_pk_mul_f32 v[44:45], v[50:51], v[44:45]
	v_cvt_pk_bf16_f32 v40, v40, v41
	v_pk_mul_f32 v[42:43], v[42:43], v[44:45]
	s_nop 0
	v_cvt_pk_bf16_f32 v41, v42, v43
	global_store_dwordx2 v[66:67], v[40:41], off offset:1696
	v_lshlrev_b32_e32 v42, 16, v164
	v_and_b32_e32 v43, 0xffff0000, v164
	v_lshlrev_b32_e32 v40, 16, v165
	v_and_b32_e32 v41, 0xffff0000, v165
	v_mul_f32_e32 v44, 0xbfb8aa3b, v42
	v_mul_f32_e32 v45, 0xbfb8aa3b, v43
	v_mul_f32_e32 v46, 0xbfb8aa3b, v40
	v_mul_f32_e32 v47, 0xbfb8aa3b, v41
	v_exp_f32_e32 v44, v44
	v_exp_f32_e32 v45, v45
	v_exp_f32_e32 v46, v46
	v_exp_f32_e32 v47, v47
	v_add_f32_e32 v44, 1.0, v44
	v_add_f32_e32 v45, 1.0, v45
	v_add_f32_e32 v46, 1.0, v46
	v_add_f32_e32 v47, 1.0, v47
	v_rcp_f32_e32 v44, v44
	v_rcp_f32_e32 v45, v45
	v_rcp_f32_e32 v46, v46
	v_rcp_f32_e32 v47, v47
	v_pk_mul_f32 v[42:43], v[44:45], v[42:43]
	s_nop 0
	v_pk_mul_f32 v[36:37], v[36:37], v[42:43]
	v_pk_mul_f32 v[40:41], v[46:47], v[40:41]
	v_cvt_pk_bf16_f32 v36, v36, v37
	v_pk_mul_f32 v[38:39], v[38:39], v[40:41]
	s_nop 0
	v_cvt_pk_bf16_f32 v37, v38, v39
	global_store_dwordx2 v[66:67], v[36:37], off offset:1728
	v_lshl_add_u64 v[36:37], v[64:65], 0, s[12:13]
	v_lshlrev_b64 v[36:37], 8, v[36:37]
	v_lshl_add_u64 v[36:37], v[156:157], 0, v[36:37]
	v_lshlrev_b32_e32 v40, 16, v166
	v_and_b32_e32 v41, 0xffff0000, v166
	v_lshlrev_b32_e32 v38, 16, v167
	v_and_b32_e32 v39, 0xffff0000, v167
	v_mul_f32_e32 v42, 0xbfb8aa3b, v40
	v_mul_f32_e32 v43, 0xbfb8aa3b, v41
	v_mul_f32_e32 v44, 0xbfb8aa3b, v38
	v_mul_f32_e32 v45, 0xbfb8aa3b, v39
	v_exp_f32_e32 v42, v42
	v_exp_f32_e32 v43, v43
	v_exp_f32_e32 v44, v44
	v_exp_f32_e32 v45, v45
	v_add_f32_e32 v42, 1.0, v42
	v_add_f32_e32 v43, 1.0, v43
	v_add_f32_e32 v44, 1.0, v44
	v_add_f32_e32 v45, 1.0, v45
	v_rcp_f32_e32 v42, v42
	v_rcp_f32_e32 v43, v43
	v_rcp_f32_e32 v44, v44
	v_rcp_f32_e32 v45, v45
	v_pk_mul_f32 v[40:41], v[42:43], v[40:41]
	s_nop 0
	v_pk_mul_f32 v[32:33], v[32:33], v[40:41]
	v_pk_mul_f32 v[38:39], v[44:45], v[38:39]
	v_cvt_pk_bf16_f32 v32, v32, v33
	v_pk_mul_f32 v[34:35], v[34:35], v[38:39]
	s_nop 0
	v_cvt_pk_bf16_f32 v33, v34, v35
	global_store_dwordx2 v[66:67], v[32:33], off offset:1760
	ds_bpermute_b32 v32, v69, v224
	s_waitcnt lgkmcnt(0)
	v_add_f32_e32 v34, v224, v32
	ds_bpermute_b32 v35, v72, v34
	v_lshlrev_b64 v[32:33], 12, v[64:65]
	v_lshl_add_u64 v[32:33], s[18:19], 0, v[32:33]
	v_lshl_add_u64 v[32:33], v[32:33], 0, s[0:1]
	v_lshl_add_u64 v[32:33], v[32:33], 0, v[136:137]
	s_waitcnt lgkmcnt(0)
	v_add_f32_e32 v34, v34, v35
	v_rcp_f32_e32 v34, v34
	s_mov_b64 s[0:1], 0
	v_lshlrev_b32_e32 v40, 16, v168
	v_and_b32_e32 v41, 0xffff0000, v168
	v_lshlrev_b32_e32 v38, 16, v169
	v_and_b32_e32 v39, 0xffff0000, v169
	v_mul_f32_e32 v35, 0xbfb8aa3b, v40
	v_mul_f32_e32 v42, 0xbfb8aa3b, v41
	v_mul_f32_e32 v43, 0xbfb8aa3b, v38
	v_mul_f32_e32 v44, 0xbfb8aa3b, v39
	v_exp_f32_e32 v35, v35
	v_exp_f32_e32 v42, v42
	v_exp_f32_e32 v43, v43
	v_exp_f32_e32 v44, v44
	v_add_f32_e32 v35, 1.0, v35
	v_add_f32_e32 v45, 1.0, v42
	v_add_f32_e32 v46, 1.0, v43
	v_add_f32_e32 v47, 1.0, v44
	v_rcp_f32_e32 v42, v35
	v_rcp_f32_e32 v43, v45
	v_rcp_f32_e32 v44, v46
	v_rcp_f32_e32 v45, v47
	v_pk_mul_f32 v[28:29], v[28:29], v[34:35] op_sel_hi:[1,0]
	v_pk_mul_f32 v[30:31], v[30:31], v[34:35] op_sel_hi:[1,0]
	v_pk_mul_f32 v[40:41], v[42:43], v[40:41]
	v_pk_mul_f32 v[38:39], v[44:45], v[38:39]
	v_pk_mul_f32 v[28:29], v[28:29], v[40:41]
	v_pk_mul_f32 v[30:31], v[30:31], v[38:39]
	v_cvt_pk_bf16_f32 v28, v28, v29
	v_cvt_pk_bf16_f32 v29, v30, v31
	global_store_dwordx2 v[32:33], v[28:29], off offset:1536
	v_lshlrev_b32_e32 v30, 16, v170
	v_and_b32_e32 v31, 0xffff0000, v170
	v_lshlrev_b32_e32 v28, 16, v171
	v_and_b32_e32 v29, 0xffff0000, v171
	v_mul_f32_e32 v35, 0xbfb8aa3b, v30
	v_mul_f32_e32 v38, 0xbfb8aa3b, v31
	v_mul_f32_e32 v39, 0xbfb8aa3b, v28
	v_mul_f32_e32 v40, 0xbfb8aa3b, v29
	v_exp_f32_e32 v35, v35
	v_exp_f32_e32 v38, v38
	v_exp_f32_e32 v39, v39
	v_exp_f32_e32 v40, v40
	v_add_f32_e32 v35, 1.0, v35
	v_add_f32_e32 v41, 1.0, v38
	v_add_f32_e32 v42, 1.0, v39
	v_add_f32_e32 v43, 1.0, v40
	v_rcp_f32_e32 v38, v35
	v_rcp_f32_e32 v39, v41
	v_rcp_f32_e32 v40, v42
	v_rcp_f32_e32 v41, v43
	v_pk_mul_f32 v[24:25], v[24:25], v[34:35] op_sel_hi:[1,0]
	v_pk_mul_f32 v[26:27], v[26:27], v[34:35] op_sel_hi:[1,0]
; __device__ __forceinline__ unsigned cvt_pk_bf16(float lo, float hi) { const f32x2 f = {lo, hi}; const bf16x2_t v = __builtin_convertvector(f, bf16x2_t); return __builtin_bit_cast(unsigned, v); }
; __device__ __forceinline__ float bflo(unsigned u) { return __uint_as_float(u << 16); }
; __device__ __forceinline__ float bfhi(unsigned u) { return __uint_as_float(u & 0xffff0000u); }
; __device__ __forceinline__ float rcp_f(float v) { return __builtin_amdgcn_rcpf(v); }
; __device__ __forceinline__ float silu_f(float v) { return v * rcp_f(1.f + __expf(-v)); }
; __device__ __forceinline__ void b_item(const Params& P, int layer, LAS unsigned char* lds, int item, int tid) {
;     ...
;     for (int u = 0; u < 2; ++u) {
;         float l = lrun[u]; l += __shfl_xor(l, 16); l += __shfl_xor(l, 32);
;         const float inv = rcp_f(l);
;         const size_t tok = tok0 + 64 * qc + 32 * th + 16 * u + c15;
;         const bf16_t* gate = pjp(proj, BG, 128, h, tok);
;         bf16_t* y = (bf16_t*)(P.ws + (layer == 0 ? WS_H : WS_D1)) + tok * DM + YB + h * 128;
; #pragma unroll
;         for (int vb = 0; vb < 8; ++vb) { const int v0 = 16 * vb + 4 * g; const u32x2 gt2 = *(const u32x2*)(gate + v0);
;             u32x2 o; o.x = cvt_pk_bf16(acco[u][vb][0] * inv * silu_f(bflo(gt2.x)), acco[u][vb][1] * inv * silu_f(bfhi(gt2.x)));
;             o.y = cvt_pk_bf16(acco[u][vb][2] * inv * silu_f(bflo(gt2.y)), acco[u][vb][3] * inv * silu_f(bfhi(gt2.y)));
;             *(u32x2*)(y + v0) = o; }
	v_pk_mul_f32 v[30:31], v[38:39], v[30:31]
	v_pk_mul_f32 v[28:29], v[40:41], v[28:29]
	v_pk_mul_f32 v[24:25], v[24:25], v[30:31]
	v_pk_mul_f32 v[26:27], v[26:27], v[28:29]
	v_cvt_pk_bf16_f32 v24, v24, v25
	v_cvt_pk_bf16_f32 v25, v26, v27
	global_store_dwordx2 v[32:33], v[24:25], off offset:1568
	v_pk_mul_f32 v[20:21], v[20:21], v[34:35] op_sel_hi:[1,0]
	v_pk_mul_f32 v[22:23], v[22:23], v[34:35] op_sel_hi:[1,0]
	v_pk_mul_f32 v[16:17], v[16:17], v[34:35] op_sel_hi:[1,0]
	v_pk_mul_f32 v[18:19], v[18:19], v[34:35] op_sel_hi:[1,0]
	v_pk_mul_f32 v[12:13], v[12:13], v[34:35] op_sel_hi:[1,0]
	v_pk_mul_f32 v[14:15], v[14:15], v[34:35] op_sel_hi:[1,0]
	v_pk_mul_f32 v[8:9], v[8:9], v[34:35] op_sel_hi:[1,0]
	v_pk_mul_f32 v[10:11], v[10:11], v[34:35] op_sel_hi:[1,0]
	v_pk_mul_f32 v[4:5], v[4:5], v[34:35] op_sel_hi:[1,0]
	v_pk_mul_f32 v[6:7], v[6:7], v[34:35] op_sel_hi:[1,0]
	v_pk_mul_f32 v[0:1], v[0:1], v[34:35] op_sel_hi:[1,0]
	v_pk_mul_f32 v[2:3], v[2:3], v[34:35] op_sel_hi:[1,0]
	v_lshlrev_b32_e32 v26, 16, v172
	v_and_b32_e32 v27, 0xffff0000, v172
	v_lshlrev_b32_e32 v24, 16, v173
	v_and_b32_e32 v25, 0xffff0000, v173
	v_mul_f32_e32 v28, 0xbfb8aa3b, v26
	v_mul_f32_e32 v29, 0xbfb8aa3b, v27
	v_mul_f32_e32 v30, 0xbfb8aa3b, v24
	v_mul_f32_e32 v31, 0xbfb8aa3b, v25
	v_exp_f32_e32 v28, v28
	v_exp_f32_e32 v29, v29
	v_exp_f32_e32 v30, v30
	v_exp_f32_e32 v31, v31
	v_add_f32_e32 v28, 1.0, v28
	v_add_f32_e32 v29, 1.0, v29
	v_add_f32_e32 v30, 1.0, v30
	v_add_f32_e32 v31, 1.0, v31
	v_rcp_f32_e32 v28, v28
	v_rcp_f32_e32 v29, v29
	v_rcp_f32_e32 v30, v30
	v_rcp_f32_e32 v31, v31
	v_pk_mul_f32 v[26:27], v[28:29], v[26:27]
	s_nop 0
	v_pk_mul_f32 v[20:21], v[20:21], v[26:27]
	v_pk_mul_f32 v[24:25], v[30:31], v[24:25]
	v_cvt_pk_bf16_f32 v20, v20, v21
	v_pk_mul_f32 v[22:23], v[22:23], v[24:25]
	s_nop 0
	v_cvt_pk_bf16_f32 v21, v22, v23
	global_store_dwordx2 v[32:33], v[20:21], off offset:1600
	v_lshlrev_b32_e32 v22, 16, v174
	v_and_b32_e32 v23, 0xffff0000, v174
	v_lshlrev_b32_e32 v20, 16, v175
	v_and_b32_e32 v21, 0xffff0000, v175
	v_mul_f32_e32 v24, 0xbfb8aa3b, v22
	v_mul_f32_e32 v25, 0xbfb8aa3b, v23
	v_mul_f32_e32 v26, 0xbfb8aa3b, v20
	v_mul_f32_e32 v27, 0xbfb8aa3b, v21
	v_exp_f32_e32 v24, v24
	v_exp_f32_e32 v25, v25
	v_exp_f32_e32 v26, v26
	v_exp_f32_e32 v27, v27
	v_add_f32_e32 v24, 1.0, v24
	v_add_f32_e32 v25, 1.0, v25
	v_add_f32_e32 v26, 1.0, v26
	v_add_f32_e32 v27, 1.0, v27
	v_rcp_f32_e32 v24, v24
	v_rcp_f32_e32 v25, v25
	v_rcp_f32_e32 v26, v26
	v_rcp_f32_e32 v27, v27
	v_pk_mul_f32 v[22:23], v[24:25], v[22:23]
	s_nop 0
	v_pk_mul_f32 v[16:17], v[16:17], v[22:23]
	v_pk_mul_f32 v[20:21], v[26:27], v[20:21]
	v_cvt_pk_bf16_f32 v16, v16, v17
	v_pk_mul_f32 v[18:19], v[18:19], v[20:21]
	s_nop 0
	v_cvt_pk_bf16_f32 v17, v18, v19
	global_store_dwordx2 v[32:33], v[16:17], off offset:1632
	v_lshlrev_b32_e32 v18, 16, v228
	v_and_b32_e32 v19, 0xffff0000, v228
	v_lshlrev_b32_e32 v16, 16, v229
	v_and_b32_e32 v17, 0xffff0000, v229
	v_mul_f32_e32 v20, 0xbfb8aa3b, v18
	v_mul_f32_e32 v21, 0xbfb8aa3b, v19
	v_mul_f32_e32 v22, 0xbfb8aa3b, v16
	v_mul_f32_e32 v23, 0xbfb8aa3b, v17
	v_exp_f32_e32 v20, v20
	v_exp_f32_e32 v21, v21
	v_exp_f32_e32 v22, v22
	v_exp_f32_e32 v23, v23
	v_add_f32_e32 v20, 1.0, v20
	v_add_f32_e32 v21, 1.0, v21
	v_add_f32_e32 v22, 1.0, v22
	v_add_f32_e32 v23, 1.0, v23
	v_rcp_f32_e32 v20, v20
	v_rcp_f32_e32 v21, v21
	v_rcp_f32_e32 v22, v22
	v_rcp_f32_e32 v23, v23
	v_pk_mul_f32 v[18:19], v[20:21], v[18:19]
	s_nop 0
	v_pk_mul_f32 v[12:13], v[12:13], v[18:19]
	v_pk_mul_f32 v[16:17], v[22:23], v[16:17]
	v_cvt_pk_bf16_f32 v12, v12, v13
	v_pk_mul_f32 v[14:15], v[14:15], v[16:17]
	s_nop 0
	v_cvt_pk_bf16_f32 v13, v14, v15
	global_store_dwordx2 v[32:33], v[12:13], off offset:1664
	v_lshlrev_b32_e32 v14, 16, v230
	v_and_b32_e32 v15, 0xffff0000, v230
	v_lshlrev_b32_e32 v12, 16, v231
	v_and_b32_e32 v13, 0xffff0000, v231
	v_mul_f32_e32 v16, 0xbfb8aa3b, v14
	v_mul_f32_e32 v17, 0xbfb8aa3b, v15
	v_mul_f32_e32 v18, 0xbfb8aa3b, v12
	v_mul_f32_e32 v19, 0xbfb8aa3b, v13
	v_exp_f32_e32 v16, v16
	v_exp_f32_e32 v17, v17
	v_exp_f32_e32 v18, v18
	v_exp_f32_e32 v19, v19
	v_add_f32_e32 v16, 1.0, v16
	v_add_f32_e32 v17, 1.0, v17
	v_add_f32_e32 v18, 1.0, v18
	v_add_f32_e32 v19, 1.0, v19
	v_rcp_f32_e32 v16, v16
	v_rcp_f32_e32 v17, v17
	v_rcp_f32_e32 v18, v18
	v_rcp_f32_e32 v19, v19
	v_pk_mul_f32 v[14:15], v[16:17], v[14:15]
	s_nop 0
	v_pk_mul_f32 v[8:9], v[8:9], v[14:15]
	v_pk_mul_f32 v[12:13], v[18:19], v[12:13]
	v_cvt_pk_bf16_f32 v8, v8, v9
	v_pk_mul_f32 v[10:11], v[10:11], v[12:13]
	s_nop 0
	v_cvt_pk_bf16_f32 v9, v10, v11
	global_store_dwordx2 v[32:33], v[8:9], off offset:1696
	v_lshlrev_b32_e32 v10, 16, v226
	v_and_b32_e32 v11, 0xffff0000, v226
	v_lshlrev_b32_e32 v8, 16, v227
	v_and_b32_e32 v9, 0xffff0000, v227
	v_mul_f32_e32 v12, 0xbfb8aa3b, v10
	v_mul_f32_e32 v13, 0xbfb8aa3b, v11
	v_mul_f32_e32 v14, 0xbfb8aa3b, v8
	v_mul_f32_e32 v15, 0xbfb8aa3b, v9
	v_exp_f32_e32 v12, v12
	v_exp_f32_e32 v13, v13
	v_exp_f32_e32 v14, v14
	v_exp_f32_e32 v15, v15
	v_add_f32_e32 v12, 1.0, v12
	v_add_f32_e32 v13, 1.0, v13
	v_add_f32_e32 v14, 1.0, v14
	v_add_f32_e32 v15, 1.0, v15
	v_rcp_f32_e32 v12, v12
	v_rcp_f32_e32 v13, v13
	v_rcp_f32_e32 v14, v14
	v_rcp_f32_e32 v15, v15
	v_pk_mul_f32 v[10:11], v[12:13], v[10:11]
	s_nop 0
	v_pk_mul_f32 v[4:5], v[4:5], v[10:11]
	v_pk_mul_f32 v[8:9], v[14:15], v[8:9]
	v_cvt_pk_bf16_f32 v4, v4, v5
	v_pk_mul_f32 v[6:7], v[6:7], v[8:9]
	s_nop 0
	v_cvt_pk_bf16_f32 v5, v6, v7
	global_store_dwordx2 v[32:33], v[4:5], off offset:1728
	v_lshlrev_b32_e32 v6, 16, v162
	v_and_b32_e32 v7, 0xffff0000, v162
	v_lshlrev_b32_e32 v4, 16, v163
	v_and_b32_e32 v5, 0xffff0000, v163
	v_mul_f32_e32 v8, 0xbfb8aa3b, v6
	v_mul_f32_e32 v9, 0xbfb8aa3b, v7
	v_mul_f32_e32 v10, 0xbfb8aa3b, v4
	v_mul_f32_e32 v11, 0xbfb8aa3b, v5
	v_exp_f32_e32 v8, v8
	v_exp_f32_e32 v9, v9
	v_exp_f32_e32 v10, v10
	v_exp_f32_e32 v11, v11
	v_add_f32_e32 v8, 1.0, v8
	v_add_f32_e32 v9, 1.0, v9
	v_add_f32_e32 v10, 1.0, v10
	v_add_f32_e32 v11, 1.0, v11
	v_rcp_f32_e32 v8, v8
	v_rcp_f32_e32 v9, v9
	v_rcp_f32_e32 v10, v10
	v_rcp_f32_e32 v11, v11
	v_pk_mul_f32 v[6:7], v[8:9], v[6:7]
	s_nop 0
	v_pk_mul_f32 v[0:1], v[0:1], v[6:7]
	v_pk_mul_f32 v[4:5], v[10:11], v[4:5]
	v_cvt_pk_bf16_f32 v0, v0, v1
	v_pk_mul_f32 v[2:3], v[2:3], v[4:5]
	s_nop 0
	v_cvt_pk_bf16_f32 v1, v2, v3
	global_store_dwordx2 v[32:33], v[0:1], off offset:1760
	s_cmp_eq_u32 s58, 0
	s_cbranch_scc1 .Lepi_loop_ret

; __device__ __forceinline__ void b_item(const Params& P, int layer, LAS unsigned char* lds, int item, int tid) {
;     ...
; #pragma unroll 1
;     for (int j = jst; j < 12; ++j) {
;         const int buf = (j - jst) & 1;
;         asm volatile("s_waitcnt vmcnt(0)" ::: "memory");
;         __syncthreads();
;         if (j + 1 < 12) B_DMA(j + 1, buf ^ 1);
;         step(j, KV + buf * 32768, KV + buf * 32768 + 16384);
;     }
.LBB0_160:
	s_or_b64 exec, exec, s[14:15]
	s_add_i32 s56, s56, 0x8000
	v_add_u32_e32 v221, -1, v221
	v_subrev_u32_e32 v222, 64, v222
	v_subrev_u32_e32 v223, 64, v223
	v_readfirstlane_b32 s58, v207
	s_nop 1
	s_sub_u32 s58, s57, s58
	s_cmp_eq_u32 s58, 1
	s_cbranch_scc1 .Lepi_hook_a
	s_cmp_eq_u32 s58, 2
	s_cbranch_scc1 .Lepi_hook_b
.Lepi_loop_ret:
	s_cmp_lt_i32 s57, 11
	s_cbranch_scc0 .LBB0_140
